# grid barrier: XCD leader releases its local workgroups right after the top-level arrival (no wait for the generation-add ack), its own L1/L2 invalidate moved after the release
# speedup vs baseline: 1.0103x; 1.0103x over previous
; __device__ __forceinline__ unsigned xb_add(unsigned* p, unsigned v) { return __hip_atomic_fetch_add(p, v, __ATOMIC_RELAXED, __HIP_MEMORY_SCOPE_AGENT); }
; __device__ __forceinline__ void xcd_barrier(const XcdBarrier& b) {
;     ...
;             __builtin_amdgcn_fence(__ATOMIC_ACQUIRE, "agent");
;             xb_add(&bar[XB_XGEN(b.x)], 1u);
;             asm volatile("s_waitcnt vmcnt(0)" ::: "memory");
.LBB0_526:
	s_or_b64 exec, exec, s[26:27]
	s_mov_b64 s[26:27], exec
	v_mbcnt_lo_u32_b32 v1, s26, 0
	v_mbcnt_hi_u32_b32 v1, s27, v1
	v_cmp_eq_u32_e32 vcc, 0, v1
	s_and_saveexec_b64 s[40:41], vcc
	s_cbranch_execz .LBB0_528
	s_bcnt1_i32_b64 s2, s[26:27]
	v_readlane_b32 s4, v254, 36
	v_mov_b32_e32 v1, s2
	v_readlane_b32 s5, v254, 37
	s_nop 4
	global_atomic_add v0, v1, s[4:5]
.LBB0_528:
	s_or_b64 exec, exec, s[40:41]
	buffer_inv sc1
	s_waitcnt vmcnt(0)
